# P9 EpiGu: row-rstd gather hoisted into peeled K-iteration (8 loads/lane, LDS handoff), epilogue reads 8 ds_read
# speedup vs baseline: 1.0165x; 1.0072x over previous
.LBB0_1224:
	v_readlane_b32 s27, v246, 0
	s_lshl_b32 s12, s12, 5
	s_add_i32 s25, s27, 0x18000
	s_and_b32 s24, s12, 0x60
	s_add_i32 s54, s25, s5
	s_mov_b64 s[12:13], 0x80
	s_lshl_b32 s17, s4, 13
	s_lshl_b32 s18, s24, 7
	v_lshl_add_u64 v[6:7], v[6:7], 0, s[12:13]
	s_mov_b32 m0, s54
	s_add_i32 s55, s54, 0x2000
	s_add_i32 s56, s48, 0x8000
	s_add_i32 s57, s48, 0xa000
	s_waitcnt vmcnt(4)
	s_barrier
	global_load_lds_dwordx4 v[6:7], off
	v_lshl_add_u64 v[4:5], v[4:5], 0, s[12:13]
	s_mov_b32 m0, s55
	s_add_u32 s14, s34, 0x40080
	global_load_lds_dwordx4 v[4:5], off
	v_lshl_add_u64 v[2:3], v[2:3], 0, s[12:13]
	s_mov_b32 m0, s56
	s_addc_u32 s15, s35, 0
	s_add_i32 s26, s27, 0x1c000
	global_load_lds_dwordx4 v[2:3], off
	v_lshl_add_u64 v[0:1], v[0:1], 0, s[12:13]
	s_mov_b32 m0, s57
	s_add_i32 s58, s26, s5
	global_load_lds_dwordx4 v[0:1], off
	v_lshl_add_u64 v[0:1], s[14:15], 0, v[128:129]
	s_mov_b32 m0, s58
	s_add_i32 s59, s58, 0x2000
	global_load_lds_dwordx4 v[0:1], off
	v_lshl_add_u64 v[0:1], s[14:15], 0, v[130:131]
	s_mov_b32 m0, s59
	v_bfe_u32 v2, v202, 4, 2
	global_load_lds_dwordx4 v[0:1], off
	v_lshlrev_b32_e32 v0, 4, v2
	v_lshlrev_b32_e32 v3, 2, v153
	v_lshl_or_b32 v1, v153, 6, v0
	v_and_b32_e32 v3, 32, v3
	v_or_b32_e32 v0, v0, v151
	v_bitop3_b32 v3, v1, s17, v3 bitop3:0xde
	v_bitop3_b32 v4, s18, v0, v155 bitop3:0xf6
	v_mul_u32_u24_e32 v0, 0x21000, v2
	v_and_b32_e32 v1, 63, v202
	v_lshl_or_b32 v160, s4, 6, v153
	v_cmp_eq_u32_e64 s[4:5], 0, v1
	v_lshlrev_b32_e32 v0, 2, v0
	v_mov_b32_e32 v1, v129
	v_lshl_add_u64 v[0:1], s[22:23], 0, v[0:1]
	s_mov_b64 s[18:19], 0x18db4000
	v_lshl_add_u64 v[132:133], v[0:1], 0, s[18:19]
	v_lshlrev_b32_e32 v0, 8, v202
	v_and_b32_e32 v0, 0xffff8000, v0
	v_lshlrev_b32_e32 v1, 11, v9
	v_or3_b32 v0, v147, v0, v1
	v_readlane_b32 s14, v246, 1
	v_add_u32_e32 v134, v0, v149
	v_lshlrev_b32_e32 v0, 4, v8
	s_ashr_i32 s61, s14, 31
	s_ashr_i32 s63, s74, 31
	v_and_b32_e32 v0, 0xffff8000, v0
	s_waitcnt vmcnt(6)
	v_readlane_b32 s15, v246, 2
	s_cmpk_gt_i32 s74, 0xef
	v_or3_b32 v0, v147, v0, v1
	s_mov_b32 s62, s14
	s_cselect_b64 s[14:15], -1, 0
	s_add_i32 s43, s74, 0xffffff10
	v_add_u32_e32 v136, v0, v149
	v_mbcnt_lo_u32_b32 v0, -1, 0
	s_mov_b32 s60, 0x21000
	s_mul_hi_u32 s64, s43, 9
	s_mul_i32 s65, s43, 9
	v_lshl_or_b32 v161, v2, 3, s24
	v_mov_b32_e32 v135, v129
	v_mov_b32_e32 v137, v129
	v_add_u32_e32 v162, s11, v4
	v_add_u32_e32 v163, s27, v3
	v_add_u32_e32 v164, s16, v4
	v_add_u32_e32 v165, s25, v4
	v_add_u32_e32 v166, s26, v4
	v_mbcnt_hi_u32_b32 v167, -1, v0
	s_mov_b32 s66, 0x42000
	s_mov_b32 s67, 0x63000
	s_waitcnt vmcnt(0)
	v_mov_b32_e32 v168, 0x358637bd
	v_readlane_b32 s92, v246, 0
	v_lshrrev_b32_e32 v203, 6, v202
	v_and_b32_e32 v247, 31, v202
	v_lshl_or_b32 v247, v203, 5, v247
	v_lshlrev_b32_e32 v247, 2, v247
	v_and_b32_e32 v203, 32, v202
	v_mul_u32_u24_e32 v203, 0x8400, v203
	v_add_u32_e32 v203, v203, v247
	s_add_i32 s92, s92, 0x20000
	s_nop 0
	v_add_u32_e32 v247, s92, v247
	s_movk_i32 s68, 0x1600
	v_mov_b64_e32 v[138:139], 0xac8
	v_mov_b64_e32 v[140:141], 0x57
	v_mov_b64_e32 v[142:143], 0xaff
	s_mov_b32 s11, 0
	s_barrier
	s_branch .LBB0_1227

.LBB0_1242:
	s_xor_b64 s[26:27], s[36:37], -1
	s_and_b64 s[36:37], s[36:37], exec
	s_cselect_b32 s11, s19, s31
	s_cselect_b32 s17, s18, s30
	s_cselect_b32 s29, s25, s35
	s_cselect_b32 s38, s24, s34
	s_add_u32 s30, s30, 0x40080
	s_addc_u32 s31, s31, 0
	s_add_u32 s39, s34, 0x100
	s_addc_u32 s40, s35, 0
	s_mov_b32 s41, -2
	ds_read_b128 v[170:173], v162
	ds_read_b128 v[174:177], v162 offset:1024
	ds_read_b128 v[178:181], v162 offset:2048
	ds_read_b128 v[182:185], v162 offset:3072
	s_add_u32 s34, s30, 0xfffc0080
	s_addc_u32 s35, s31, -1
	s_cmp_eq_u32 s41, 12
	s_cselect_b32 s37, s11, s35
	s_cselect_b32 s36, s17, s34
	s_cselect_b32 s35, s29, s40
	s_cselect_b32 s34, s38, s39
	v_lshl_add_u64 v[144:145], s[30:31], 0, v[134:135]
	s_add_i32 m0, s48, 0xc000
	ds_read_b128 v[186:189], v163
	ds_read_b128 v[190:193], v163 offset:1024
	ds_read_b128 v[194:197], v163 offset:2048
	ds_read_b128 v[198:201], v163 offset:3072
	ds_read_b128 v[204:207], v163 offset:4096
	ds_read_b128 v[208:211], v163 offset:5120
	ds_read_b128 v[212:215], v163 offset:6144
	ds_read_b128 v[216:219], v163 offset:7168
	global_load_lds_dwordx4 v[144:145], off
	v_lshl_add_u64 v[144:145], s[30:31], 0, v[136:137]
	s_add_i32 m0, s48, 0xe000
	s_nop 0
	global_load_lds_dwordx4 v[144:145], off
	ds_read_b128 v[220:223], v164
	ds_read_b128 v[224:227], v164 offset:1024
	ds_read_b128 v[228:231], v164 offset:2048
	ds_read_b128 v[232:235], v164 offset:3072
	s_waitcnt lgkmcnt(0)
	s_waitcnt vmcnt(8)
	s_barrier
	s_setprio 1
	v_mfma_f32_16x16x32_bf16 v[124:127], v[170:173], v[186:189], 0
	v_mfma_f32_16x16x32_bf16 v[120:123], v[178:181], v[186:189], 0
	v_mfma_f32_16x16x32_bf16 v[112:115], v[170:173], v[194:197], 0
	v_mfma_f32_16x16x32_bf16 v[104:107], v[178:181], v[194:197], 0
	v_mfma_f32_16x16x32_bf16 v[96:99], v[170:173], v[204:207], 0
	v_mfma_f32_16x16x32_bf16 v[88:91], v[178:181], v[204:207], 0
	v_mfma_f32_16x16x32_bf16 v[80:83], v[170:173], v[212:215], 0
	v_mfma_f32_16x16x32_bf16 v[72:75], v[178:181], v[212:215], 0
	v_mfma_f32_16x16x32_bf16 v[124:127], v[174:177], v[190:193], v[124:127]
	v_mfma_f32_16x16x32_bf16 v[120:123], v[182:185], v[190:193], v[120:123]
	v_mfma_f32_16x16x32_bf16 v[112:115], v[174:177], v[198:201], v[112:115]
	v_mfma_f32_16x16x32_bf16 v[104:107], v[182:185], v[198:201], v[104:107]
	v_mfma_f32_16x16x32_bf16 v[96:99], v[174:177], v[208:211], v[96:99]
	v_mfma_f32_16x16x32_bf16 v[88:91], v[182:185], v[208:211], v[88:91]
	v_mfma_f32_16x16x32_bf16 v[80:83], v[174:177], v[216:219], v[80:83]
	v_mfma_f32_16x16x32_bf16 v[72:75], v[182:185], v[216:219], v[72:75]
	v_mfma_f32_16x16x32_bf16 v[116:119], v[220:223], v[186:189], 0
	v_mfma_f32_16x16x32_bf16 v[108:111], v[228:231], v[186:189], 0
	v_mfma_f32_16x16x32_bf16 v[100:103], v[220:223], v[194:197], 0
	v_mfma_f32_16x16x32_bf16 v[92:95], v[228:231], v[194:197], 0
	v_mfma_f32_16x16x32_bf16 v[84:87], v[220:223], v[204:207], 0
	v_mfma_f32_16x16x32_bf16 v[76:79], v[228:231], v[204:207], 0
	v_mfma_f32_16x16x32_bf16 v[68:71], v[220:223], v[212:215], 0
	v_mfma_f32_16x16x32_bf16 v[64:67], v[228:231], v[212:215], 0
	v_mfma_f32_16x16x32_bf16 v[116:119], v[224:227], v[190:193], v[116:119]
	v_mfma_f32_16x16x32_bf16 v[108:111], v[232:235], v[190:193], v[108:111]
	v_mfma_f32_16x16x32_bf16 v[100:103], v[224:227], v[198:201], v[100:103]
	v_mfma_f32_16x16x32_bf16 v[92:95], v[232:235], v[198:201], v[92:95]
	v_mfma_f32_16x16x32_bf16 v[84:87], v[224:227], v[208:211], v[84:87]
	v_mfma_f32_16x16x32_bf16 v[76:79], v[232:235], v[208:211], v[76:79]
	v_mfma_f32_16x16x32_bf16 v[68:71], v[224:227], v[216:219], v[68:71]
	v_mfma_f32_16x16x32_bf16 v[64:67], v[232:235], v[216:219], v[64:67]
	s_setprio 0
	s_barrier
	s_lshl_b32 s75, s42, 10
	s_add_u32 s76, s22, s75
	s_addc_u32 s77, s23, 0
	s_add_u32 s76, s76, 0x18db4000
	s_addc_u32 s77, s77, 0
	s_add_u32 s78, s76, 0x21000
	s_addc_u32 s79, s77, 0
	s_add_u32 s80, s78, 0x21000
	s_addc_u32 s81, s79, 0
	s_add_u32 s82, s80, 0x21000
	s_addc_u32 s83, s81, 0
	s_add_u32 s84, s82, 0x21000
	s_addc_u32 s85, s83, 0
	s_add_u32 s86, s84, 0x21000
	s_addc_u32 s87, s85, 0
	s_add_u32 s88, s86, 0x21000
	s_addc_u32 s89, s87, 0
	s_add_u32 s90, s88, 0x21000
	s_addc_u32 s91, s89, 0
	global_load_dword v242, v203, s[76:77]
	global_load_dword v243, v203, s[78:79]
	global_load_dword v250, v203, s[80:81]
	global_load_dword v251, v203, s[82:83]
	global_load_dword v252, v203, s[84:85]
	global_load_dword v253, v203, s[86:87]
	global_load_dword v254, v203, s[88:89]
	global_load_dword v255, v203, s[90:91]
	ds_read_b128 v[186:189], v163 offset:16384
	ds_read_b128 v[190:193], v163 offset:17408
	ds_read_b128 v[194:197], v163 offset:18432
	ds_read_b128 v[198:201], v163 offset:19456
	ds_read_b128 v[204:207], v163 offset:20480
	ds_read_b128 v[208:211], v163 offset:21504
	ds_read_b128 v[212:215], v163 offset:22528
	ds_read_b128 v[216:219], v163 offset:23552
	s_mov_b32 m0, s46
	v_lshl_add_u64 v[144:145], s[34:35], 0, v[128:129]
	global_load_lds_dwordx4 v[144:145], off
	v_lshl_add_u64 v[236:237], s[34:35], 0, v[130:131]
	s_mov_b32 m0, s47
	s_nop 0
	global_load_lds_dwordx4 v[236:237], off
	s_mov_b32 m0, s48
	v_lshl_add_u64 v[238:239], s[36:37], 0, v[128:129]
	global_load_lds_dwordx4 v[238:239], off
	v_lshl_add_u64 v[240:241], s[36:37], 0, v[130:131]
	s_mov_b32 m0, s49
	s_nop 0
	global_load_lds_dwordx4 v[240:241], off
	s_add_u32 s72, s34, 0x40000
	s_addc_u32 s73, s35, 0
	s_mov_b32 m0, s50
	v_lshl_add_u64 v[248:249], s[72:73], 0, v[128:129]
	global_load_lds_dwordx4 v[248:249], off
	v_lshl_add_u64 v[248:249], s[72:73], 0, v[130:131]
	s_mov_b32 m0, s51
	s_nop 0
	global_load_lds_dwordx4 v[248:249], off
	s_waitcnt lgkmcnt(0)
	s_waitcnt vmcnt(16)
	s_barrier
	s_setprio 1
	v_mfma_f32_16x16x32_bf16 v[60:63], v[170:173], v[186:189], 0
	v_mfma_f32_16x16x32_bf16 v[56:59], v[178:181], v[186:189], 0
	v_mfma_f32_16x16x32_bf16 v[48:51], v[170:173], v[194:197], 0
	v_mfma_f32_16x16x32_bf16 v[40:43], v[178:181], v[194:197], 0
	v_mfma_f32_16x16x32_bf16 v[32:35], v[170:173], v[204:207], 0
	v_mfma_f32_16x16x32_bf16 v[24:27], v[178:181], v[204:207], 0
	v_mfma_f32_16x16x32_bf16 v[16:19], v[170:173], v[212:215], 0
	v_mfma_f32_16x16x32_bf16 v[8:11], v[178:181], v[212:215], 0
	v_mfma_f32_16x16x32_bf16 v[60:63], v[174:177], v[190:193], v[60:63]
	v_mfma_f32_16x16x32_bf16 v[56:59], v[182:185], v[190:193], v[56:59]
	v_mfma_f32_16x16x32_bf16 v[48:51], v[174:177], v[198:201], v[48:51]
	v_mfma_f32_16x16x32_bf16 v[40:43], v[182:185], v[198:201], v[40:43]
	v_mfma_f32_16x16x32_bf16 v[32:35], v[174:177], v[208:211], v[32:35]
	v_mfma_f32_16x16x32_bf16 v[24:27], v[182:185], v[208:211], v[24:27]
	v_mfma_f32_16x16x32_bf16 v[16:19], v[174:177], v[216:219], v[16:19]
	v_mfma_f32_16x16x32_bf16 v[8:11], v[182:185], v[216:219], v[8:11]
	v_mfma_f32_16x16x32_bf16 v[52:55], v[220:223], v[186:189], 0
	v_mfma_f32_16x16x32_bf16 v[44:47], v[228:231], v[186:189], 0
	v_mfma_f32_16x16x32_bf16 v[36:39], v[220:223], v[194:197], 0
	v_mfma_f32_16x16x32_bf16 v[28:31], v[228:231], v[194:197], 0
	v_mfma_f32_16x16x32_bf16 v[20:23], v[220:223], v[204:207], 0
	v_mfma_f32_16x16x32_bf16 v[12:15], v[228:231], v[204:207], 0
	v_mfma_f32_16x16x32_bf16 v[4:7], v[220:223], v[212:215], 0
	v_mfma_f32_16x16x32_bf16 v[0:3], v[228:231], v[212:215], 0
	v_mfma_f32_16x16x32_bf16 v[52:55], v[224:227], v[190:193], v[52:55]
	v_mfma_f32_16x16x32_bf16 v[44:47], v[232:235], v[190:193], v[44:47]
	v_mfma_f32_16x16x32_bf16 v[36:39], v[224:227], v[198:201], v[36:39]
	v_mfma_f32_16x16x32_bf16 v[28:31], v[232:235], v[198:201], v[28:31]
	v_mfma_f32_16x16x32_bf16 v[20:23], v[224:227], v[208:211], v[20:23]
	v_mfma_f32_16x16x32_bf16 v[12:15], v[232:235], v[208:211], v[12:15]
	v_mfma_f32_16x16x32_bf16 v[4:7], v[224:227], v[216:219], v[4:7]
	v_mfma_f32_16x16x32_bf16 v[0:3], v[232:235], v[216:219], v[0:3]
	s_setprio 0
	s_barrier
	ds_read_b128 v[170:173], v165
	ds_read_b128 v[174:177], v165 offset:1024
	ds_read_b128 v[178:181], v165 offset:2048
	ds_read_b128 v[182:185], v165 offset:3072
	s_add_u32 s36, s36, 0x40000
	s_addc_u32 s37, s37, 0
	s_mov_b32 m0, s52
	v_lshl_add_u64 v[220:221], s[36:37], 0, v[128:129]
	ds_read_b128 v[186:189], v163 offset:32768
	ds_read_b128 v[190:193], v163 offset:33792
	ds_read_b128 v[194:197], v163 offset:34816
	ds_read_b128 v[198:201], v163 offset:35840
	ds_read_b128 v[204:207], v163 offset:36864
	ds_read_b128 v[208:211], v163 offset:37888
	ds_read_b128 v[212:215], v163 offset:38912
	ds_read_b128 v[216:219], v163 offset:39936
	global_load_lds_dwordx4 v[220:221], off
	v_lshl_add_u64 v[220:221], s[36:37], 0, v[130:131]
	s_mov_b32 m0, s53
	s_nop 0
	global_load_lds_dwordx4 v[220:221], off
	ds_read_b128 v[220:223], v166
	ds_read_b128 v[224:227], v166 offset:1024
	ds_read_b128 v[228:231], v166 offset:2048
	ds_read_b128 v[232:235], v166 offset:3072
	s_waitcnt lgkmcnt(0)
	s_waitcnt vmcnt(16)
	s_barrier
	s_setprio 1
	v_mfma_f32_16x16x32_bf16 v[124:127], v[170:173], v[186:189], v[124:127]
	v_mfma_f32_16x16x32_bf16 v[120:123], v[178:181], v[186:189], v[120:123]
	v_mfma_f32_16x16x32_bf16 v[112:115], v[170:173], v[194:197], v[112:115]
	v_mfma_f32_16x16x32_bf16 v[104:107], v[178:181], v[194:197], v[104:107]
	v_mfma_f32_16x16x32_bf16 v[96:99], v[170:173], v[204:207], v[96:99]
	v_mfma_f32_16x16x32_bf16 v[88:91], v[178:181], v[204:207], v[88:91]
	v_mfma_f32_16x16x32_bf16 v[80:83], v[170:173], v[212:215], v[80:83]
	v_mfma_f32_16x16x32_bf16 v[72:75], v[178:181], v[212:215], v[72:75]
	v_mfma_f32_16x16x32_bf16 v[124:127], v[174:177], v[190:193], v[124:127]
	v_mfma_f32_16x16x32_bf16 v[120:123], v[182:185], v[190:193], v[120:123]
	v_mfma_f32_16x16x32_bf16 v[112:115], v[174:177], v[198:201], v[112:115]
	v_mfma_f32_16x16x32_bf16 v[104:107], v[182:185], v[198:201], v[104:107]
	v_mfma_f32_16x16x32_bf16 v[96:99], v[174:177], v[208:211], v[96:99]
	v_mfma_f32_16x16x32_bf16 v[88:91], v[182:185], v[208:211], v[88:91]
	v_mfma_f32_16x16x32_bf16 v[80:83], v[174:177], v[216:219], v[80:83]
	v_mfma_f32_16x16x32_bf16 v[72:75], v[182:185], v[216:219], v[72:75]
	v_mfma_f32_16x16x32_bf16 v[116:119], v[220:223], v[186:189], v[116:119]
	v_mfma_f32_16x16x32_bf16 v[108:111], v[228:231], v[186:189], v[108:111]
	v_mfma_f32_16x16x32_bf16 v[100:103], v[220:223], v[194:197], v[100:103]
	v_mfma_f32_16x16x32_bf16 v[92:95], v[228:231], v[194:197], v[92:95]
	v_mfma_f32_16x16x32_bf16 v[84:87], v[220:223], v[204:207], v[84:87]
	v_mfma_f32_16x16x32_bf16 v[76:79], v[228:231], v[204:207], v[76:79]
	v_mfma_f32_16x16x32_bf16 v[68:71], v[220:223], v[212:215], v[68:71]
	v_mfma_f32_16x16x32_bf16 v[64:67], v[228:231], v[212:215], v[64:67]
	v_mfma_f32_16x16x32_bf16 v[116:119], v[224:227], v[190:193], v[116:119]
	v_mfma_f32_16x16x32_bf16 v[108:111], v[232:235], v[190:193], v[108:111]
	v_mfma_f32_16x16x32_bf16 v[100:103], v[224:227], v[198:201], v[100:103]
	v_mfma_f32_16x16x32_bf16 v[92:95], v[232:235], v[198:201], v[92:95]
	v_mfma_f32_16x16x32_bf16 v[84:87], v[224:227], v[208:211], v[84:87]
	v_mfma_f32_16x16x32_bf16 v[76:79], v[232:235], v[208:211], v[76:79]
	v_mfma_f32_16x16x32_bf16 v[68:71], v[224:227], v[216:219], v[68:71]
	v_mfma_f32_16x16x32_bf16 v[64:67], v[232:235], v[216:219], v[64:67]
	s_setprio 0
	s_barrier
	ds_read_b128 v[186:189], v163 offset:49152
	ds_read_b128 v[190:193], v163 offset:50176
	ds_read_b128 v[194:197], v163 offset:51200
	ds_read_b128 v[198:201], v163 offset:52224
	ds_read_b128 v[204:207], v163 offset:53248
	ds_read_b128 v[208:211], v163 offset:54272
	ds_read_b128 v[212:215], v163 offset:55296
	ds_read_b128 v[216:219], v163 offset:56320
	s_mov_b32 m0, s54
	v_lshl_add_u64 v[144:145], v[144:145], 0, s[12:13]
	global_load_lds_dwordx4 v[144:145], off
	v_lshl_add_u64 v[144:145], v[236:237], 0, s[12:13]
	s_mov_b32 m0, s55
	s_nop 0
	global_load_lds_dwordx4 v[144:145], off
	s_mov_b32 m0, s56
	v_lshl_add_u64 v[144:145], v[238:239], 0, s[12:13]
	global_load_lds_dwordx4 v[144:145], off
	v_lshl_add_u64 v[144:145], v[240:241], 0, s[12:13]
	s_mov_b32 m0, s57
	s_nop 0
	global_load_lds_dwordx4 v[144:145], off
	s_add_u32 s34, s34, 0x40080
	s_addc_u32 s35, s35, 0
	s_mov_b32 m0, s58
	v_lshl_add_u64 v[144:145], s[34:35], 0, v[128:129]
	global_load_lds_dwordx4 v[144:145], off
	v_lshl_add_u64 v[144:145], s[34:35], 0, v[130:131]
	s_mov_b32 m0, s59
	s_nop 0
	global_load_lds_dwordx4 v[144:145], off
	s_waitcnt lgkmcnt(0)
	s_waitcnt vmcnt(8)
	s_barrier
	s_setprio 1
	v_mfma_f32_16x16x32_bf16 v[60:63], v[170:173], v[186:189], v[60:63]
	v_mfma_f32_16x16x32_bf16 v[56:59], v[178:181], v[186:189], v[56:59]
	v_add_f32_e32 v242, v242, v243
	v_mfma_f32_16x16x32_bf16 v[48:51], v[170:173], v[194:197], v[48:51]
	v_add_f32_e32 v250, v250, v251
	v_mfma_f32_16x16x32_bf16 v[40:43], v[178:181], v[194:197], v[40:43]
	v_add_f32_e32 v252, v252, v253
	v_mfma_f32_16x16x32_bf16 v[32:35], v[170:173], v[204:207], v[32:35]
	v_add_f32_e32 v254, v254, v255
	v_mfma_f32_16x16x32_bf16 v[24:27], v[178:181], v[204:207], v[24:27]
	v_add_f32_e32 v242, v242, v250
	v_mfma_f32_16x16x32_bf16 v[16:19], v[170:173], v[212:215], v[16:19]
	v_add_f32_e32 v252, v252, v254
	v_mfma_f32_16x16x32_bf16 v[8:11], v[178:181], v[212:215], v[8:11]
	v_add_f32_e32 v242, v242, v252
	v_mfma_f32_16x16x32_bf16 v[60:63], v[174:177], v[190:193], v[60:63]
	v_mov_b32_e32 v243, v242
	v_mfma_f32_16x16x32_bf16 v[56:59], v[182:185], v[190:193], v[56:59]
	v_mfma_f32_16x16x32_bf16 v[48:51], v[174:177], v[198:201], v[48:51]
	s_nop 1
	v_permlane32_swap_b32_e32 v242, v243
	v_mfma_f32_16x16x32_bf16 v[40:43], v[182:185], v[198:201], v[40:43]
	v_mfma_f32_16x16x32_bf16 v[32:35], v[174:177], v[208:211], v[32:35]
	v_add_f32_e32 v242, v242, v243
	v_mfma_f32_16x16x32_bf16 v[24:27], v[182:185], v[208:211], v[24:27]
	v_fmamk_f32 v242, v242, 0x3a800000, v168
	v_mfma_f32_16x16x32_bf16 v[16:19], v[174:177], v[216:219], v[16:19]
	v_rsq_f32_e32 v242, v242
	v_mfma_f32_16x16x32_bf16 v[8:11], v[182:185], v[216:219], v[8:11]
	v_mfma_f32_16x16x32_bf16 v[52:55], v[220:223], v[186:189], v[52:55]
	s_nop 0
	ds_write_b32 v247, v242
	v_mfma_f32_16x16x32_bf16 v[44:47], v[228:231], v[186:189], v[44:47]
	v_mfma_f32_16x16x32_bf16 v[36:39], v[220:223], v[194:197], v[36:39]
	v_mfma_f32_16x16x32_bf16 v[28:31], v[228:231], v[194:197], v[28:31]
	v_mfma_f32_16x16x32_bf16 v[20:23], v[220:223], v[204:207], v[20:23]
	v_mfma_f32_16x16x32_bf16 v[12:15], v[228:231], v[204:207], v[12:15]
	v_mfma_f32_16x16x32_bf16 v[4:7], v[220:223], v[212:215], v[4:7]
	v_mfma_f32_16x16x32_bf16 v[0:3], v[228:231], v[212:215], v[0:3]
	v_mfma_f32_16x16x32_bf16 v[52:55], v[224:227], v[190:193], v[52:55]
	v_mfma_f32_16x16x32_bf16 v[44:47], v[232:235], v[190:193], v[44:47]
	v_mfma_f32_16x16x32_bf16 v[36:39], v[224:227], v[198:201], v[36:39]
	v_mfma_f32_16x16x32_bf16 v[28:31], v[232:235], v[198:201], v[28:31]
	v_mfma_f32_16x16x32_bf16 v[20:23], v[224:227], v[208:211], v[20:23]
	v_mfma_f32_16x16x32_bf16 v[12:15], v[232:235], v[208:211], v[12:15]
	v_mfma_f32_16x16x32_bf16 v[4:7], v[224:227], v[216:219], v[4:7]
	v_mfma_f32_16x16x32_bf16 v[0:3], v[232:235], v[216:219], v[0:3]
	s_setprio 0
	s_add_i32 s41, s41, 2
	s_add_u32 s30, s30, 0x100
	s_addc_u32 s31, s31, 0
	s_add_u32 s39, s39, 0x100
	s_addc_u32 s40, s40, 0
	s_cmp_gt_u32 s41, 13
	s_barrier
.LBB0_1243:
	ds_read_b128 v[170:173], v162
	ds_read_b128 v[174:177], v162 offset:1024
	ds_read_b128 v[178:181], v162 offset:2048
	ds_read_b128 v[182:185], v162 offset:3072
	s_add_u32 s34, s30, 0xfffc0080
	s_addc_u32 s35, s31, -1
	s_cmp_eq_u32 s41, 12
	s_cselect_b32 s37, s11, s35
	s_cselect_b32 s36, s17, s34
	s_cselect_b32 s35, s29, s40
	s_cselect_b32 s34, s38, s39
	v_lshl_add_u64 v[144:145], s[30:31], 0, v[134:135]
	s_add_i32 m0, s48, 0xc000
	ds_read_b128 v[186:189], v163
	ds_read_b128 v[190:193], v163 offset:1024
	ds_read_b128 v[194:197], v163 offset:2048
	ds_read_b128 v[198:201], v163 offset:3072
	ds_read_b128 v[204:207], v163 offset:4096
	ds_read_b128 v[208:211], v163 offset:5120
	ds_read_b128 v[212:215], v163 offset:6144
	ds_read_b128 v[216:219], v163 offset:7168
	global_load_lds_dwordx4 v[144:145], off
	v_lshl_add_u64 v[144:145], s[30:31], 0, v[136:137]
	s_add_i32 m0, s48, 0xe000
	s_nop 0
	global_load_lds_dwordx4 v[144:145], off
	ds_read_b128 v[220:223], v164
	ds_read_b128 v[224:227], v164 offset:1024
	ds_read_b128 v[228:231], v164 offset:2048
	ds_read_b128 v[232:235], v164 offset:3072
	s_waitcnt lgkmcnt(0)
	s_waitcnt vmcnt(8)
	s_barrier
	s_setprio 1
	v_mfma_f32_16x16x32_bf16 v[124:127], v[170:173], v[186:189], v[124:127]
	v_mfma_f32_16x16x32_bf16 v[120:123], v[178:181], v[186:189], v[120:123]
	v_mfma_f32_16x16x32_bf16 v[112:115], v[170:173], v[194:197], v[112:115]
	v_mfma_f32_16x16x32_bf16 v[104:107], v[178:181], v[194:197], v[104:107]
	v_mfma_f32_16x16x32_bf16 v[96:99], v[170:173], v[204:207], v[96:99]
	v_mfma_f32_16x16x32_bf16 v[88:91], v[178:181], v[204:207], v[88:91]
	v_mfma_f32_16x16x32_bf16 v[80:83], v[170:173], v[212:215], v[80:83]
	v_mfma_f32_16x16x32_bf16 v[72:75], v[178:181], v[212:215], v[72:75]
	v_mfma_f32_16x16x32_bf16 v[124:127], v[174:177], v[190:193], v[124:127]
	v_mfma_f32_16x16x32_bf16 v[120:123], v[182:185], v[190:193], v[120:123]
	v_mfma_f32_16x16x32_bf16 v[112:115], v[174:177], v[198:201], v[112:115]
	v_mfma_f32_16x16x32_bf16 v[104:107], v[182:185], v[198:201], v[104:107]
	v_mfma_f32_16x16x32_bf16 v[96:99], v[174:177], v[208:211], v[96:99]
	v_mfma_f32_16x16x32_bf16 v[88:91], v[182:185], v[208:211], v[88:91]
	v_mfma_f32_16x16x32_bf16 v[80:83], v[174:177], v[216:219], v[80:83]
	v_mfma_f32_16x16x32_bf16 v[72:75], v[182:185], v[216:219], v[72:75]
	v_mfma_f32_16x16x32_bf16 v[116:119], v[220:223], v[186:189], v[116:119]
	v_mfma_f32_16x16x32_bf16 v[108:111], v[228:231], v[186:189], v[108:111]
	v_mfma_f32_16x16x32_bf16 v[100:103], v[220:223], v[194:197], v[100:103]
	v_mfma_f32_16x16x32_bf16 v[92:95], v[228:231], v[194:197], v[92:95]
	v_mfma_f32_16x16x32_bf16 v[84:87], v[220:223], v[204:207], v[84:87]
	v_mfma_f32_16x16x32_bf16 v[76:79], v[228:231], v[204:207], v[76:79]
	v_mfma_f32_16x16x32_bf16 v[68:71], v[220:223], v[212:215], v[68:71]
	v_mfma_f32_16x16x32_bf16 v[64:67], v[228:231], v[212:215], v[64:67]
	v_mfma_f32_16x16x32_bf16 v[116:119], v[224:227], v[190:193], v[116:119]
	v_mfma_f32_16x16x32_bf16 v[108:111], v[232:235], v[190:193], v[108:111]
	v_mfma_f32_16x16x32_bf16 v[100:103], v[224:227], v[198:201], v[100:103]
	v_mfma_f32_16x16x32_bf16 v[92:95], v[232:235], v[198:201], v[92:95]
	v_mfma_f32_16x16x32_bf16 v[84:87], v[224:227], v[208:211], v[84:87]
	v_mfma_f32_16x16x32_bf16 v[76:79], v[232:235], v[208:211], v[76:79]
	v_mfma_f32_16x16x32_bf16 v[68:71], v[224:227], v[216:219], v[68:71]
	v_mfma_f32_16x16x32_bf16 v[64:67], v[232:235], v[216:219], v[64:67]
	s_setprio 0
	s_barrier
	ds_read_b128 v[186:189], v163 offset:16384
	ds_read_b128 v[190:193], v163 offset:17408
	ds_read_b128 v[194:197], v163 offset:18432
	ds_read_b128 v[198:201], v163 offset:19456
	ds_read_b128 v[204:207], v163 offset:20480
	ds_read_b128 v[208:211], v163 offset:21504
	ds_read_b128 v[212:215], v163 offset:22528
	ds_read_b128 v[216:219], v163 offset:23552
	s_mov_b32 m0, s46
	v_lshl_add_u64 v[144:145], s[34:35], 0, v[128:129]
	global_load_lds_dwordx4 v[144:145], off
	v_lshl_add_u64 v[236:237], s[34:35], 0, v[130:131]
	s_mov_b32 m0, s47
	s_nop 0
	global_load_lds_dwordx4 v[236:237], off
	s_mov_b32 m0, s48
	v_lshl_add_u64 v[238:239], s[36:37], 0, v[128:129]
	global_load_lds_dwordx4 v[238:239], off
	v_lshl_add_u64 v[240:241], s[36:37], 0, v[130:131]
	s_mov_b32 m0, s49
	s_nop 0
	global_load_lds_dwordx4 v[240:241], off
	s_add_u32 s72, s34, 0x40000
	s_addc_u32 s73, s35, 0
	s_mov_b32 m0, s50
	v_lshl_add_u64 v[248:249], s[72:73], 0, v[128:129]
	global_load_lds_dwordx4 v[248:249], off
	v_lshl_add_u64 v[248:249], s[72:73], 0, v[130:131]
	s_mov_b32 m0, s51
	s_nop 0
	global_load_lds_dwordx4 v[248:249], off
	s_waitcnt lgkmcnt(0)
	s_waitcnt vmcnt(8)
	s_barrier
	s_setprio 1
	v_mfma_f32_16x16x32_bf16 v[60:63], v[170:173], v[186:189], v[60:63]
	v_mfma_f32_16x16x32_bf16 v[56:59], v[178:181], v[186:189], v[56:59]
	v_mfma_f32_16x16x32_bf16 v[48:51], v[170:173], v[194:197], v[48:51]
	v_mfma_f32_16x16x32_bf16 v[40:43], v[178:181], v[194:197], v[40:43]
	v_mfma_f32_16x16x32_bf16 v[32:35], v[170:173], v[204:207], v[32:35]
	v_mfma_f32_16x16x32_bf16 v[24:27], v[178:181], v[204:207], v[24:27]
	v_mfma_f32_16x16x32_bf16 v[16:19], v[170:173], v[212:215], v[16:19]
	v_mfma_f32_16x16x32_bf16 v[8:11], v[178:181], v[212:215], v[8:11]
	v_mfma_f32_16x16x32_bf16 v[60:63], v[174:177], v[190:193], v[60:63]
	v_mfma_f32_16x16x32_bf16 v[56:59], v[182:185], v[190:193], v[56:59]
	v_mfma_f32_16x16x32_bf16 v[48:51], v[174:177], v[198:201], v[48:51]
	v_mfma_f32_16x16x32_bf16 v[40:43], v[182:185], v[198:201], v[40:43]
	v_mfma_f32_16x16x32_bf16 v[32:35], v[174:177], v[208:211], v[32:35]
	v_mfma_f32_16x16x32_bf16 v[24:27], v[182:185], v[208:211], v[24:27]
	v_mfma_f32_16x16x32_bf16 v[16:19], v[174:177], v[216:219], v[16:19]
	v_mfma_f32_16x16x32_bf16 v[8:11], v[182:185], v[216:219], v[8:11]
	v_mfma_f32_16x16x32_bf16 v[52:55], v[220:223], v[186:189], v[52:55]
	v_mfma_f32_16x16x32_bf16 v[44:47], v[228:231], v[186:189], v[44:47]
	v_mfma_f32_16x16x32_bf16 v[36:39], v[220:223], v[194:197], v[36:39]
	v_mfma_f32_16x16x32_bf16 v[28:31], v[228:231], v[194:197], v[28:31]
	v_mfma_f32_16x16x32_bf16 v[20:23], v[220:223], v[204:207], v[20:23]
	v_mfma_f32_16x16x32_bf16 v[12:15], v[228:231], v[204:207], v[12:15]
	v_mfma_f32_16x16x32_bf16 v[4:7], v[220:223], v[212:215], v[4:7]
	v_mfma_f32_16x16x32_bf16 v[0:3], v[228:231], v[212:215], v[0:3]
	v_mfma_f32_16x16x32_bf16 v[52:55], v[224:227], v[190:193], v[52:55]
	v_mfma_f32_16x16x32_bf16 v[44:47], v[232:235], v[190:193], v[44:47]
	v_mfma_f32_16x16x32_bf16 v[36:39], v[224:227], v[198:201], v[36:39]
	v_mfma_f32_16x16x32_bf16 v[28:31], v[232:235], v[198:201], v[28:31]
	v_mfma_f32_16x16x32_bf16 v[20:23], v[224:227], v[208:211], v[20:23]
	v_mfma_f32_16x16x32_bf16 v[12:15], v[232:235], v[208:211], v[12:15]
	v_mfma_f32_16x16x32_bf16 v[4:7], v[224:227], v[216:219], v[4:7]
	v_mfma_f32_16x16x32_bf16 v[0:3], v[232:235], v[216:219], v[0:3]
	s_setprio 0
	s_barrier
	ds_read_b128 v[170:173], v165
	ds_read_b128 v[174:177], v165 offset:1024
	ds_read_b128 v[178:181], v165 offset:2048
	ds_read_b128 v[182:185], v165 offset:3072
	s_add_u32 s36, s36, 0x40000
	s_addc_u32 s37, s37, 0
	s_mov_b32 m0, s52
	v_lshl_add_u64 v[220:221], s[36:37], 0, v[128:129]
	ds_read_b128 v[186:189], v163 offset:32768
	ds_read_b128 v[190:193], v163 offset:33792
	ds_read_b128 v[194:197], v163 offset:34816
	ds_read_b128 v[198:201], v163 offset:35840
	ds_read_b128 v[204:207], v163 offset:36864
	ds_read_b128 v[208:211], v163 offset:37888
	ds_read_b128 v[212:215], v163 offset:38912
	ds_read_b128 v[216:219], v163 offset:39936
	global_load_lds_dwordx4 v[220:221], off
	v_lshl_add_u64 v[220:221], s[36:37], 0, v[130:131]
	s_mov_b32 m0, s53
	s_nop 0
	global_load_lds_dwordx4 v[220:221], off
	ds_read_b128 v[220:223], v166
	ds_read_b128 v[224:227], v166 offset:1024
	ds_read_b128 v[228:231], v166 offset:2048
	ds_read_b128 v[232:235], v166 offset:3072
	s_waitcnt lgkmcnt(0)
	s_waitcnt vmcnt(8)
	s_barrier
	s_setprio 1
	v_mfma_f32_16x16x32_bf16 v[124:127], v[170:173], v[186:189], v[124:127]
	v_mfma_f32_16x16x32_bf16 v[120:123], v[178:181], v[186:189], v[120:123]
	v_mfma_f32_16x16x32_bf16 v[112:115], v[170:173], v[194:197], v[112:115]
	v_mfma_f32_16x16x32_bf16 v[104:107], v[178:181], v[194:197], v[104:107]
	v_mfma_f32_16x16x32_bf16 v[96:99], v[170:173], v[204:207], v[96:99]
	v_mfma_f32_16x16x32_bf16 v[88:91], v[178:181], v[204:207], v[88:91]
	v_mfma_f32_16x16x32_bf16 v[80:83], v[170:173], v[212:215], v[80:83]
	v_mfma_f32_16x16x32_bf16 v[72:75], v[178:181], v[212:215], v[72:75]
	v_mfma_f32_16x16x32_bf16 v[124:127], v[174:177], v[190:193], v[124:127]
	v_mfma_f32_16x16x32_bf16 v[120:123], v[182:185], v[190:193], v[120:123]
	v_mfma_f32_16x16x32_bf16 v[112:115], v[174:177], v[198:201], v[112:115]
	v_mfma_f32_16x16x32_bf16 v[104:107], v[182:185], v[198:201], v[104:107]
	v_mfma_f32_16x16x32_bf16 v[96:99], v[174:177], v[208:211], v[96:99]
	v_mfma_f32_16x16x32_bf16 v[88:91], v[182:185], v[208:211], v[88:91]
	v_mfma_f32_16x16x32_bf16 v[80:83], v[174:177], v[216:219], v[80:83]
	v_mfma_f32_16x16x32_bf16 v[72:75], v[182:185], v[216:219], v[72:75]
	v_mfma_f32_16x16x32_bf16 v[116:119], v[220:223], v[186:189], v[116:119]
	v_mfma_f32_16x16x32_bf16 v[108:111], v[228:231], v[186:189], v[108:111]
	v_mfma_f32_16x16x32_bf16 v[100:103], v[220:223], v[194:197], v[100:103]
	v_mfma_f32_16x16x32_bf16 v[92:95], v[228:231], v[194:197], v[92:95]
	v_mfma_f32_16x16x32_bf16 v[84:87], v[220:223], v[204:207], v[84:87]
	v_mfma_f32_16x16x32_bf16 v[76:79], v[228:231], v[204:207], v[76:79]
	v_mfma_f32_16x16x32_bf16 v[68:71], v[220:223], v[212:215], v[68:71]
	v_mfma_f32_16x16x32_bf16 v[64:67], v[228:231], v[212:215], v[64:67]
	v_mfma_f32_16x16x32_bf16 v[116:119], v[224:227], v[190:193], v[116:119]
	v_mfma_f32_16x16x32_bf16 v[108:111], v[232:235], v[190:193], v[108:111]
	v_mfma_f32_16x16x32_bf16 v[100:103], v[224:227], v[198:201], v[100:103]
	v_mfma_f32_16x16x32_bf16 v[92:95], v[232:235], v[198:201], v[92:95]
	v_mfma_f32_16x16x32_bf16 v[84:87], v[224:227], v[208:211], v[84:87]
	v_mfma_f32_16x16x32_bf16 v[76:79], v[232:235], v[208:211], v[76:79]
	v_mfma_f32_16x16x32_bf16 v[68:71], v[224:227], v[216:219], v[68:71]
	v_mfma_f32_16x16x32_bf16 v[64:67], v[232:235], v[216:219], v[64:67]
	s_setprio 0
	s_barrier
	ds_read_b128 v[186:189], v163 offset:49152
	ds_read_b128 v[190:193], v163 offset:50176
	ds_read_b128 v[194:197], v163 offset:51200
	ds_read_b128 v[198:201], v163 offset:52224
	ds_read_b128 v[204:207], v163 offset:53248
	ds_read_b128 v[208:211], v163 offset:54272
	ds_read_b128 v[212:215], v163 offset:55296
	ds_read_b128 v[216:219], v163 offset:56320
	s_mov_b32 m0, s54
	v_lshl_add_u64 v[144:145], v[144:145], 0, s[12:13]
	global_load_lds_dwordx4 v[144:145], off
	v_lshl_add_u64 v[144:145], v[236:237], 0, s[12:13]
	s_mov_b32 m0, s55
	s_nop 0
	global_load_lds_dwordx4 v[144:145], off
	s_mov_b32 m0, s56
	v_lshl_add_u64 v[144:145], v[238:239], 0, s[12:13]
	global_load_lds_dwordx4 v[144:145], off
	v_lshl_add_u64 v[144:145], v[240:241], 0, s[12:13]
	s_mov_b32 m0, s57
	s_nop 0
	global_load_lds_dwordx4 v[144:145], off
	s_add_u32 s34, s34, 0x40080
	s_addc_u32 s35, s35, 0
	s_mov_b32 m0, s58
	v_lshl_add_u64 v[144:145], s[34:35], 0, v[128:129]
	global_load_lds_dwordx4 v[144:145], off
	v_lshl_add_u64 v[144:145], s[34:35], 0, v[130:131]
	s_mov_b32 m0, s59
	s_nop 0
	global_load_lds_dwordx4 v[144:145], off
	s_waitcnt lgkmcnt(0)
	s_waitcnt vmcnt(8)
	s_barrier
	s_setprio 1
	v_mfma_f32_16x16x32_bf16 v[60:63], v[170:173], v[186:189], v[60:63]
	v_mfma_f32_16x16x32_bf16 v[56:59], v[178:181], v[186:189], v[56:59]
	v_mfma_f32_16x16x32_bf16 v[48:51], v[170:173], v[194:197], v[48:51]
	v_mfma_f32_16x16x32_bf16 v[40:43], v[178:181], v[194:197], v[40:43]
	v_mfma_f32_16x16x32_bf16 v[32:35], v[170:173], v[204:207], v[32:35]
	v_mfma_f32_16x16x32_bf16 v[24:27], v[178:181], v[204:207], v[24:27]
	v_mfma_f32_16x16x32_bf16 v[16:19], v[170:173], v[212:215], v[16:19]
	v_mfma_f32_16x16x32_bf16 v[8:11], v[178:181], v[212:215], v[8:11]
	v_mfma_f32_16x16x32_bf16 v[60:63], v[174:177], v[190:193], v[60:63]
	v_mfma_f32_16x16x32_bf16 v[56:59], v[182:185], v[190:193], v[56:59]
	v_mfma_f32_16x16x32_bf16 v[48:51], v[174:177], v[198:201], v[48:51]
	v_mfma_f32_16x16x32_bf16 v[40:43], v[182:185], v[198:201], v[40:43]
	v_mfma_f32_16x16x32_bf16 v[32:35], v[174:177], v[208:211], v[32:35]
	v_mfma_f32_16x16x32_bf16 v[24:27], v[182:185], v[208:211], v[24:27]
	v_mfma_f32_16x16x32_bf16 v[16:19], v[174:177], v[216:219], v[16:19]
	v_mfma_f32_16x16x32_bf16 v[8:11], v[182:185], v[216:219], v[8:11]
	v_mfma_f32_16x16x32_bf16 v[52:55], v[220:223], v[186:189], v[52:55]
	v_mfma_f32_16x16x32_bf16 v[44:47], v[228:231], v[186:189], v[44:47]
	v_mfma_f32_16x16x32_bf16 v[36:39], v[220:223], v[194:197], v[36:39]
	v_mfma_f32_16x16x32_bf16 v[28:31], v[228:231], v[194:197], v[28:31]
	v_mfma_f32_16x16x32_bf16 v[20:23], v[220:223], v[204:207], v[20:23]
	v_mfma_f32_16x16x32_bf16 v[12:15], v[228:231], v[204:207], v[12:15]
	v_mfma_f32_16x16x32_bf16 v[4:7], v[220:223], v[212:215], v[4:7]
	v_mfma_f32_16x16x32_bf16 v[0:3], v[228:231], v[212:215], v[0:3]
	v_mfma_f32_16x16x32_bf16 v[52:55], v[224:227], v[190:193], v[52:55]
	v_mfma_f32_16x16x32_bf16 v[44:47], v[232:235], v[190:193], v[44:47]
	v_mfma_f32_16x16x32_bf16 v[36:39], v[224:227], v[198:201], v[36:39]
	v_mfma_f32_16x16x32_bf16 v[28:31], v[232:235], v[198:201], v[28:31]
	v_mfma_f32_16x16x32_bf16 v[20:23], v[224:227], v[208:211], v[20:23]
	v_mfma_f32_16x16x32_bf16 v[12:15], v[232:235], v[208:211], v[12:15]
	v_mfma_f32_16x16x32_bf16 v[4:7], v[224:227], v[216:219], v[4:7]
	v_mfma_f32_16x16x32_bf16 v[0:3], v[232:235], v[216:219], v[0:3]
	s_setprio 0
	s_add_i32 s41, s41, 2
	s_add_u32 s30, s30, 0x100
	s_addc_u32 s31, s31, 0
	s_add_u32 s39, s39, 0x100
	s_addc_u32 s40, s40, 0
	s_cmp_gt_u32 s41, 13
	s_barrier
	s_cbranch_scc0 .LBB0_1243
	v_lshlrev_b32_e32 v170, 2, v160
	v_add_u32_e32 v170, s92, v170
	ds_read_b32 v174, v170
	ds_read_b32 v176, v170 offset:64
	ds_read_b32 v156, v170 offset:128
	ds_read_b32 v154, v170 offset:192
	ds_read_b32 v152, v170 offset:512
	ds_read_b32 v150, v170 offset:576
	ds_read_b32 v148, v170 offset:640
	ds_read_b32 v146, v170 offset:704
	v_lshl_add_u32 v144, s42, 8, v160
	v_add_u32_e32 v145, 0x80, v144
	s_cmpk_lt_i32 s42, 0x80
	s_waitcnt lgkmcnt(0)
	v_pk_mul_f32 v[124:125], v[124:125], v[174:175] op_sel_hi:[1,0]
	v_mul_f32_e32 v172, 0xbfb8aa3b, v125
	v_exp_f32_e32 v173, v172
	v_mul_f32_e32 v169, 0xbfb8aa3b, v124
	v_exp_f32_e32 v169, v169
	v_pk_mul_f32 v[126:127], v[126:127], v[174:175] op_sel_hi:[1,0]
	v_pk_mul_f32 v[118:119], v[118:119], v[174:175] op_sel_hi:[1,0]
	v_add_f32_e32 v169, 1.0, v169
	v_rcp_f32_e32 v172, v169
	v_add_f32_e32 v169, 1.0, v173
	v_mul_f32_e32 v173, 0xbfb8aa3b, v126
	v_exp_f32_e32 v175, v173
	v_mul_f32_e32 v173, 0xbfb8aa3b, v127
	v_exp_f32_e32 v177, v173
	v_rcp_f32_e32 v173, v169
	v_add_f32_e32 v169, 1.0, v175
	v_rcp_f32_e32 v178, v169
	v_add_f32_e32 v169, 1.0, v177
	v_rcp_f32_e32 v179, v169
	v_pk_mul_f32 v[116:117], v[116:117], v[174:175] op_sel_hi:[1,0]
	v_pk_mul_f32 v[124:125], v[124:125], v[172:173]
	v_pk_mul_f32 v[120:121], v[120:121], v[174:175] op_sel_hi:[1,0]
	v_pk_mul_f32 v[116:117], v[116:117], v[124:125]
	v_pk_mul_f32 v[124:125], v[126:127], v[178:179]
	v_pk_mul_f32 v[122:123], v[122:123], v[174:175] op_sel_hi:[1,0]
	v_pk_mul_f32 v[118:119], v[118:119], v[124:125]
	v_mul_f32_e32 v124, 0xbfb8aa3b, v120
	v_mul_f32_e32 v125, 0xbfb8aa3b, v121
	v_exp_f32_e32 v124, v124
	v_exp_f32_e32 v125, v125
	v_mul_f32_e32 v126, 0xbfb8aa3b, v122
	v_mul_f32_e32 v127, 0xbfb8aa3b, v123
	v_exp_f32_e32 v126, v126
	v_exp_f32_e32 v127, v127
	v_add_f32_e32 v124, 1.0, v124
	v_add_f32_e32 v125, 1.0, v125
	v_rcp_f32_e32 v124, v124
	v_rcp_f32_e32 v125, v125
	v_add_f32_e32 v126, 1.0, v126
	v_add_f32_e32 v127, 1.0, v127
	v_rcp_f32_e32 v126, v126
	v_rcp_f32_e32 v127, v127
	v_pk_mul_f32 v[108:109], v[108:109], v[174:175] op_sel_hi:[1,0]
	v_pk_mul_f32 v[120:121], v[120:121], v[124:125]
	v_lshl_or_b32 v170, s28, 7, v161
	v_pk_mul_f32 v[110:111], v[110:111], v[174:175] op_sel_hi:[1,0]
	v_pk_mul_f32 v[108:109], v[108:109], v[120:121]
	v_pk_mul_f32 v[120:121], v[122:123], v[126:127]
	v_ashrrev_i32_e32 v171, 31, v170
	v_pk_mul_f32 v[110:111], v[110:111], v[120:121]
	v_cvt_pk_bf16_f32 v116, v116, v117
	v_cvt_pk_bf16_f32 v117, v118, v119
	v_cvt_pk_bf16_f32 v118, v108, v109
	v_mov_b64_e32 v[108:109], s[6:7]
	v_cvt_pk_bf16_f32 v119, v110, v111
	v_mad_i64_i32 v[120:121], s[28:29], v144, s68, v[108:109]
	v_lshlrev_b64 v[110:111], 1, v[170:171]
	v_lshl_add_u64 v[120:121], v[120:121], 0, v[110:111]
	v_pk_mul_f32 v[112:113], v[112:113], v[176:177] op_sel_hi:[1,0]
	global_store_dwordx4 v[120:121], v[116:119], off
	v_pk_mul_f32 v[114:115], v[114:115], v[176:177] op_sel_hi:[1,0]
	v_pk_mul_f32 v[100:101], v[100:101], v[176:177] op_sel_hi:[1,0]
	v_mul_f32_e32 v116, 0xbfb8aa3b, v112
	v_mul_f32_e32 v117, 0xbfb8aa3b, v113
	v_exp_f32_e32 v116, v116
	v_exp_f32_e32 v117, v117
	v_mul_f32_e32 v118, 0xbfb8aa3b, v114
	v_mul_f32_e32 v119, 0xbfb8aa3b, v115
	v_exp_f32_e32 v118, v118
	v_exp_f32_e32 v119, v119
	v_add_f32_e32 v116, 1.0, v116
	v_add_f32_e32 v117, 1.0, v117
	v_rcp_f32_e32 v116, v116
	v_rcp_f32_e32 v117, v117
	v_add_f32_e32 v118, 1.0, v118
	v_add_f32_e32 v119, 1.0, v119
	v_rcp_f32_e32 v118, v118
	v_rcp_f32_e32 v119, v119
	v_pk_mul_f32 v[112:113], v[112:113], v[116:117]
	v_pk_mul_f32 v[102:103], v[102:103], v[176:177] op_sel_hi:[1,0]
	v_pk_mul_f32 v[100:101], v[100:101], v[112:113]
	v_pk_mul_f32 v[112:113], v[114:115], v[118:119]
	v_pk_mul_f32 v[104:105], v[104:105], v[176:177] op_sel_hi:[1,0]
	v_pk_mul_f32 v[102:103], v[102:103], v[112:113]
	v_pk_mul_f32 v[106:107], v[106:107], v[176:177] op_sel_hi:[1,0]
	v_mul_f32_e32 v112, 0xbfb8aa3b, v104
	v_mul_f32_e32 v113, 0xbfb8aa3b, v105
	v_exp_f32_e32 v112, v112
	v_exp_f32_e32 v113, v113
	v_mul_f32_e32 v114, 0xbfb8aa3b, v106
	v_mul_f32_e32 v115, 0xbfb8aa3b, v107
	v_exp_f32_e32 v114, v114
	v_exp_f32_e32 v115, v115
	v_add_f32_e32 v112, 1.0, v112
	v_add_f32_e32 v113, 1.0, v113
	v_rcp_f32_e32 v112, v112
	v_rcp_f32_e32 v113, v113
	v_add_f32_e32 v114, 1.0, v114
	v_add_f32_e32 v115, 1.0, v115
	v_rcp_f32_e32 v114, v114
	v_rcp_f32_e32 v115, v115
	v_pk_mul_f32 v[92:93], v[92:93], v[176:177] op_sel_hi:[1,0]
	v_pk_mul_f32 v[104:105], v[104:105], v[112:113]
	v_pk_mul_f32 v[94:95], v[94:95], v[176:177] op_sel_hi:[1,0]
	v_pk_mul_f32 v[104:105], v[92:93], v[104:105]
	v_pk_mul_f32 v[92:93], v[106:107], v[114:115]
	v_or_b32_e32 v112, 16, v144
	v_pk_mul_f32 v[106:107], v[94:95], v[92:93]
	v_cvt_pk_bf16_f32 v92, v100, v101
	v_mad_i64_i32 v[100:101], s[28:29], v112, s68, v[108:109]
	v_cvt_pk_bf16_f32 v93, v102, v103
	v_cvt_pk_bf16_f32 v94, v104, v105
	v_cvt_pk_bf16_f32 v95, v106, v107
	v_lshl_add_u64 v[100:101], v[100:101], 0, v[110:111]
	global_store_dwordx4 v[100:101], v[92:95], off
	v_pk_mul_f32 v[86:87], v[86:87], v[156:157] op_sel_hi:[1,0]
	v_pk_mul_f32 v[88:89], v[88:89], v[156:157] op_sel_hi:[1,0]
	v_pk_mul_f32 v[92:93], v[98:99], v[156:157] op_sel_hi:[1,0]
	v_pk_mul_f32 v[94:95], v[96:97], v[156:157] op_sel_hi:[1,0]
	v_mul_f32_e32 v98, 0xbfb8aa3b, v92
	v_mul_f32_e32 v99, 0xbfb8aa3b, v93
	v_mul_f32_e32 v96, 0xbfb8aa3b, v94
	v_mul_f32_e32 v97, 0xbfb8aa3b, v95
	v_exp_f32_e32 v98, v98
	v_exp_f32_e32 v99, v99
	v_exp_f32_e32 v96, v96
	v_exp_f32_e32 v97, v97
	v_add_f32_e32 v98, 1.0, v98
	v_add_f32_e32 v99, 1.0, v99
	v_add_f32_e32 v96, 1.0, v96
	v_add_f32_e32 v97, 1.0, v97
	v_rcp_f32_e32 v98, v98
	v_rcp_f32_e32 v99, v99
	v_rcp_f32_e32 v96, v96
	v_rcp_f32_e32 v97, v97
	v_pk_mul_f32 v[84:85], v[84:85], v[156:157] op_sel_hi:[1,0]
	v_pk_mul_f32 v[92:93], v[92:93], v[98:99]
	v_pk_mul_f32 v[90:91], v[90:91], v[156:157] op_sel_hi:[1,0]
	v_pk_mul_f32 v[94:95], v[94:95], v[96:97]
	v_pk_mul_f32 v[86:87], v[86:87], v[92:93]
	v_mul_f32_e32 v92, 0xbfb8aa3b, v88
	v_mul_f32_e32 v93, 0xbfb8aa3b, v89
	v_pk_mul_f32 v[84:85], v[84:85], v[94:95]
	v_exp_f32_e32 v92, v92
	v_exp_f32_e32 v93, v93
	v_mul_f32_e32 v94, 0xbfb8aa3b, v90
	v_mul_f32_e32 v95, 0xbfb8aa3b, v91
	v_exp_f32_e32 v94, v94
	v_exp_f32_e32 v95, v95
	v_add_f32_e32 v92, 1.0, v92
	v_add_f32_e32 v93, 1.0, v93
	v_rcp_f32_e32 v92, v92
	v_rcp_f32_e32 v93, v93
	v_add_f32_e32 v94, 1.0, v94
	v_add_f32_e32 v95, 1.0, v95
	v_rcp_f32_e32 v94, v94
	v_rcp_f32_e32 v95, v95
	v_pk_mul_f32 v[76:77], v[76:77], v[156:157] op_sel_hi:[1,0]
	v_pk_mul_f32 v[88:89], v[88:89], v[92:93]
	v_pk_mul_f32 v[78:79], v[78:79], v[156:157] op_sel_hi:[1,0]
	v_pk_mul_f32 v[88:89], v[76:77], v[88:89]
	v_pk_mul_f32 v[76:77], v[90:91], v[94:95]
	v_or_b32_e32 v92, 32, v144
	v_pk_mul_f32 v[90:91], v[78:79], v[76:77]
	v_cvt_pk_bf16_f32 v76, v84, v85
	v_mad_i64_i32 v[84:85], s[28:29], v92, s68, v[108:109]
	v_cvt_pk_bf16_f32 v77, v86, v87
	v_cvt_pk_bf16_f32 v78, v88, v89
	v_cvt_pk_bf16_f32 v79, v90, v91
	v_lshl_add_u64 v[84:85], v[84:85], 0, v[110:111]
	global_store_dwordx4 v[84:85], v[76:79], off
	v_pk_mul_f32 v[70:71], v[70:71], v[154:155] op_sel_hi:[1,0]
	v_pk_mul_f32 v[72:73], v[72:73], v[154:155] op_sel_hi:[1,0]
	v_pk_mul_f32 v[76:77], v[82:83], v[154:155] op_sel_hi:[1,0]
	v_pk_mul_f32 v[78:79], v[80:81], v[154:155] op_sel_hi:[1,0]
	v_mul_f32_e32 v82, 0xbfb8aa3b, v76
	v_mul_f32_e32 v83, 0xbfb8aa3b, v77
	v_mul_f32_e32 v80, 0xbfb8aa3b, v78
	v_mul_f32_e32 v81, 0xbfb8aa3b, v79
	v_exp_f32_e32 v82, v82
	v_exp_f32_e32 v83, v83
	v_exp_f32_e32 v80, v80
	v_exp_f32_e32 v81, v81
	v_add_f32_e32 v82, 1.0, v82
	v_add_f32_e32 v83, 1.0, v83
	v_add_f32_e32 v80, 1.0, v80
	v_add_f32_e32 v81, 1.0, v81
	v_rcp_f32_e32 v82, v82
	v_rcp_f32_e32 v83, v83
	v_rcp_f32_e32 v80, v80
	v_rcp_f32_e32 v81, v81
	v_pk_mul_f32 v[68:69], v[68:69], v[154:155] op_sel_hi:[1,0]
	v_pk_mul_f32 v[76:77], v[76:77], v[82:83]
	v_pk_mul_f32 v[74:75], v[74:75], v[154:155] op_sel_hi:[1,0]
	v_pk_mul_f32 v[78:79], v[78:79], v[80:81]
	v_pk_mul_f32 v[70:71], v[70:71], v[76:77]
	v_mul_f32_e32 v76, 0xbfb8aa3b, v72
	v_mul_f32_e32 v77, 0xbfb8aa3b, v73
	v_pk_mul_f32 v[68:69], v[68:69], v[78:79]
	v_exp_f32_e32 v76, v76
	v_exp_f32_e32 v77, v77
	v_mul_f32_e32 v78, 0xbfb8aa3b, v74
	v_mul_f32_e32 v79, 0xbfb8aa3b, v75
	v_exp_f32_e32 v78, v78
	v_exp_f32_e32 v79, v79
	v_add_f32_e32 v76, 1.0, v76
	v_add_f32_e32 v77, 1.0, v77
	v_rcp_f32_e32 v76, v76
	v_rcp_f32_e32 v77, v77
	v_add_f32_e32 v78, 1.0, v78
	v_add_f32_e32 v79, 1.0, v79
	v_rcp_f32_e32 v78, v78
	v_rcp_f32_e32 v79, v79
	v_pk_mul_f32 v[64:65], v[64:65], v[154:155] op_sel_hi:[1,0]
	v_pk_mul_f32 v[72:73], v[72:73], v[76:77]
	v_pk_mul_f32 v[66:67], v[66:67], v[154:155] op_sel_hi:[1,0]
	v_pk_mul_f32 v[72:73], v[64:65], v[72:73]
	v_pk_mul_f32 v[64:65], v[74:75], v[78:79]
	v_or_b32_e32 v76, 48, v144
	v_pk_mul_f32 v[74:75], v[66:67], v[64:65]
	v_cvt_pk_bf16_f32 v64, v68, v69
	v_mad_i64_i32 v[68:69], s[28:29], v76, s68, v[108:109]
	v_cvt_pk_bf16_f32 v65, v70, v71
	v_cvt_pk_bf16_f32 v66, v72, v73
	v_cvt_pk_bf16_f32 v67, v74, v75
	v_lshl_add_u64 v[68:69], v[68:69], 0, v[110:111]
	v_pk_mul_f32 v[60:61], v[60:61], v[152:153] op_sel_hi:[1,0]
	global_store_dwordx4 v[68:69], v[64:67], off
	v_pk_mul_f32 v[62:63], v[62:63], v[152:153] op_sel_hi:[1,0]
	v_pk_mul_f32 v[52:53], v[52:53], v[152:153] op_sel_hi:[1,0]
	v_mul_f32_e32 v64, 0xbfb8aa3b, v60
	v_mul_f32_e32 v65, 0xbfb8aa3b, v61
	v_exp_f32_e32 v64, v64
	v_exp_f32_e32 v65, v65
	v_mul_f32_e32 v66, 0xbfb8aa3b, v62
	v_mul_f32_e32 v67, 0xbfb8aa3b, v63
	v_exp_f32_e32 v66, v66
	v_exp_f32_e32 v67, v67
	v_add_f32_e32 v64, 1.0, v64
	v_add_f32_e32 v65, 1.0, v65
	v_rcp_f32_e32 v64, v64
	v_rcp_f32_e32 v65, v65
	v_add_f32_e32 v66, 1.0, v66
	v_add_f32_e32 v67, 1.0, v67
	v_rcp_f32_e32 v66, v66
	v_rcp_f32_e32 v67, v67
	v_pk_mul_f32 v[60:61], v[60:61], v[64:65]
	v_pk_mul_f32 v[54:55], v[54:55], v[152:153] op_sel_hi:[1,0]
	v_pk_mul_f32 v[52:53], v[52:53], v[60:61]
	v_pk_mul_f32 v[60:61], v[62:63], v[66:67]
	v_pk_mul_f32 v[56:57], v[56:57], v[152:153] op_sel_hi:[1,0]
	v_pk_mul_f32 v[54:55], v[54:55], v[60:61]
	v_pk_mul_f32 v[58:59], v[58:59], v[152:153] op_sel_hi:[1,0]
	v_mul_f32_e32 v60, 0xbfb8aa3b, v56
	v_mul_f32_e32 v61, 0xbfb8aa3b, v57
	v_exp_f32_e32 v60, v60
	v_exp_f32_e32 v61, v61
	v_mul_f32_e32 v62, 0xbfb8aa3b, v58
	v_mul_f32_e32 v63, 0xbfb8aa3b, v59
	v_exp_f32_e32 v62, v62
	v_exp_f32_e32 v63, v63
	v_add_f32_e32 v60, 1.0, v60
	v_add_f32_e32 v61, 1.0, v61
	v_rcp_f32_e32 v60, v60
	v_rcp_f32_e32 v61, v61
	v_add_f32_e32 v62, 1.0, v62
	v_add_f32_e32 v63, 1.0, v63
	v_rcp_f32_e32 v62, v62
	v_rcp_f32_e32 v63, v63
	v_pk_mul_f32 v[44:45], v[44:45], v[152:153] op_sel_hi:[1,0]
	v_pk_mul_f32 v[56:57], v[56:57], v[60:61]
	v_pk_mul_f32 v[46:47], v[46:47], v[152:153] op_sel_hi:[1,0]
	v_pk_mul_f32 v[56:57], v[44:45], v[56:57]
	v_pk_mul_f32 v[44:45], v[58:59], v[62:63]
	v_pk_mul_f32 v[38:39], v[38:39], v[150:151] op_sel_hi:[1,0]
	v_pk_mul_f32 v[58:59], v[46:47], v[44:45]
	v_cvt_pk_bf16_f32 v44, v52, v53
	v_mad_i64_i32 v[52:53], s[28:29], v145, s68, v[108:109]
	v_cvt_pk_bf16_f32 v45, v54, v55
	v_cvt_pk_bf16_f32 v46, v56, v57
	v_cvt_pk_bf16_f32 v47, v58, v59
	v_lshl_add_u64 v[52:53], v[52:53], 0, v[110:111]
	global_store_dwordx4 v[52:53], v[44:47], off
	v_pk_mul_f32 v[40:41], v[40:41], v[150:151] op_sel_hi:[1,0]
	v_pk_mul_f32 v[36:37], v[36:37], v[150:151] op_sel_hi:[1,0]
	v_pk_mul_f32 v[44:45], v[50:51], v[150:151] op_sel_hi:[1,0]
	v_pk_mul_f32 v[46:47], v[48:49], v[150:151] op_sel_hi:[1,0]
	v_mul_f32_e32 v50, 0xbfb8aa3b, v44
	v_mul_f32_e32 v51, 0xbfb8aa3b, v45
	v_mul_f32_e32 v48, 0xbfb8aa3b, v46
	v_mul_f32_e32 v49, 0xbfb8aa3b, v47
	v_exp_f32_e32 v50, v50
	v_exp_f32_e32 v51, v51
	v_exp_f32_e32 v48, v48
	v_exp_f32_e32 v49, v49
	v_add_f32_e32 v50, 1.0, v50
	v_add_f32_e32 v51, 1.0, v51
	v_add_f32_e32 v48, 1.0, v48
	v_add_f32_e32 v49, 1.0, v49
	v_rcp_f32_e32 v50, v50
	v_rcp_f32_e32 v51, v51
	v_rcp_f32_e32 v48, v48
	v_rcp_f32_e32 v49, v49
	v_pk_mul_f32 v[42:43], v[42:43], v[150:151] op_sel_hi:[1,0]
	v_pk_mul_f32 v[44:45], v[44:45], v[50:51]
	v_pk_mul_f32 v[46:47], v[46:47], v[48:49]
	v_pk_mul_f32 v[38:39], v[38:39], v[44:45]
	v_mul_f32_e32 v44, 0xbfb8aa3b, v40
	v_mul_f32_e32 v45, 0xbfb8aa3b, v41
	v_pk_mul_f32 v[36:37], v[36:37], v[46:47]
	v_exp_f32_e32 v44, v44
	v_exp_f32_e32 v45, v45
	v_mul_f32_e32 v46, 0xbfb8aa3b, v42
	v_mul_f32_e32 v47, 0xbfb8aa3b, v43
	v_exp_f32_e32 v46, v46
	v_exp_f32_e32 v47, v47
	v_add_f32_e32 v44, 1.0, v44
	v_add_f32_e32 v45, 1.0, v45
	v_rcp_f32_e32 v44, v44
	v_rcp_f32_e32 v45, v45
	v_add_f32_e32 v46, 1.0, v46
	v_add_f32_e32 v47, 1.0, v47
	v_rcp_f32_e32 v46, v46
	v_rcp_f32_e32 v47, v47
	v_pk_mul_f32 v[28:29], v[28:29], v[150:151] op_sel_hi:[1,0]
	v_pk_mul_f32 v[40:41], v[40:41], v[44:45]
	v_pk_mul_f32 v[30:31], v[30:31], v[150:151] op_sel_hi:[1,0]
	v_pk_mul_f32 v[40:41], v[28:29], v[40:41]
	v_pk_mul_f32 v[28:29], v[42:43], v[46:47]
	v_add_u32_e32 v44, 0x90, v144
	v_pk_mul_f32 v[42:43], v[30:31], v[28:29]
	v_cvt_pk_bf16_f32 v28, v36, v37
	v_mad_i64_i32 v[36:37], s[28:29], v44, s68, v[108:109]
	v_cvt_pk_bf16_f32 v29, v38, v39
	v_cvt_pk_bf16_f32 v30, v40, v41
	v_cvt_pk_bf16_f32 v31, v42, v43
	v_lshl_add_u64 v[36:37], v[36:37], 0, v[110:111]
	global_store_dwordx4 v[36:37], v[28:31], off
	v_pk_mul_f32 v[22:23], v[22:23], v[148:149] op_sel_hi:[1,0]
	v_pk_mul_f32 v[24:25], v[24:25], v[148:149] op_sel_hi:[1,0]
	v_pk_mul_f32 v[28:29], v[34:35], v[148:149] op_sel_hi:[1,0]
	v_pk_mul_f32 v[30:31], v[32:33], v[148:149] op_sel_hi:[1,0]
	v_mul_f32_e32 v34, 0xbfb8aa3b, v28
	v_mul_f32_e32 v35, 0xbfb8aa3b, v29
	v_mul_f32_e32 v32, 0xbfb8aa3b, v30
	v_mul_f32_e32 v33, 0xbfb8aa3b, v31
	v_exp_f32_e32 v34, v34
	v_exp_f32_e32 v35, v35
	v_exp_f32_e32 v32, v32
	v_exp_f32_e32 v33, v33
	v_add_f32_e32 v34, 1.0, v34
	v_add_f32_e32 v35, 1.0, v35
	v_add_f32_e32 v32, 1.0, v32
	v_add_f32_e32 v33, 1.0, v33
	v_rcp_f32_e32 v34, v34
	v_rcp_f32_e32 v35, v35
	v_rcp_f32_e32 v32, v32
	v_rcp_f32_e32 v33, v33
	v_pk_mul_f32 v[20:21], v[20:21], v[148:149] op_sel_hi:[1,0]
	v_pk_mul_f32 v[28:29], v[28:29], v[34:35]
	v_pk_mul_f32 v[26:27], v[26:27], v[148:149] op_sel_hi:[1,0]
	v_pk_mul_f32 v[30:31], v[30:31], v[32:33]
	v_pk_mul_f32 v[22:23], v[22:23], v[28:29]
	v_mul_f32_e32 v28, 0xbfb8aa3b, v24
	v_mul_f32_e32 v29, 0xbfb8aa3b, v25
	v_pk_mul_f32 v[20:21], v[20:21], v[30:31]
	v_exp_f32_e32 v28, v28
	v_exp_f32_e32 v29, v29
	v_mul_f32_e32 v30, 0xbfb8aa3b, v26
	v_mul_f32_e32 v31, 0xbfb8aa3b, v27
	v_exp_f32_e32 v30, v30
	v_exp_f32_e32 v31, v31
	v_add_f32_e32 v28, 1.0, v28
	v_add_f32_e32 v29, 1.0, v29
	v_rcp_f32_e32 v28, v28
	v_rcp_f32_e32 v29, v29
	v_add_f32_e32 v30, 1.0, v30
	v_add_f32_e32 v31, 1.0, v31
	v_rcp_f32_e32 v30, v30
	v_rcp_f32_e32 v31, v31
	v_pk_mul_f32 v[12:13], v[12:13], v[148:149] op_sel_hi:[1,0]
	v_pk_mul_f32 v[24:25], v[24:25], v[28:29]
	v_pk_mul_f32 v[14:15], v[14:15], v[148:149] op_sel_hi:[1,0]
	v_pk_mul_f32 v[24:25], v[12:13], v[24:25]
	v_pk_mul_f32 v[12:13], v[26:27], v[30:31]
	v_add_u32_e32 v28, 0xa0, v144
	v_pk_mul_f32 v[26:27], v[14:15], v[12:13]
	v_cvt_pk_bf16_f32 v12, v20, v21
	v_mad_i64_i32 v[20:21], s[28:29], v28, s68, v[108:109]
	v_cvt_pk_bf16_f32 v13, v22, v23
	v_cvt_pk_bf16_f32 v14, v24, v25
	v_cvt_pk_bf16_f32 v15, v26, v27
	v_lshl_add_u64 v[20:21], v[20:21], 0, v[110:111]
	global_store_dwordx4 v[20:21], v[12:15], off
	v_pk_mul_f32 v[6:7], v[6:7], v[146:147] op_sel_hi:[1,0]
	v_pk_mul_f32 v[8:9], v[8:9], v[146:147] op_sel_hi:[1,0]
	v_pk_mul_f32 v[12:13], v[18:19], v[146:147] op_sel_hi:[1,0]
	v_pk_mul_f32 v[14:15], v[16:17], v[146:147] op_sel_hi:[1,0]
	v_mul_f32_e32 v18, 0xbfb8aa3b, v12
	v_mul_f32_e32 v19, 0xbfb8aa3b, v13
	v_mul_f32_e32 v16, 0xbfb8aa3b, v14
	v_mul_f32_e32 v17, 0xbfb8aa3b, v15
	v_exp_f32_e32 v18, v18
	v_exp_f32_e32 v19, v19
	v_exp_f32_e32 v16, v16
	v_exp_f32_e32 v17, v17
	v_add_f32_e32 v18, 1.0, v18
	v_add_f32_e32 v19, 1.0, v19
	v_add_f32_e32 v16, 1.0, v16
	v_add_f32_e32 v17, 1.0, v17
	v_rcp_f32_e32 v18, v18
	v_rcp_f32_e32 v19, v19
	v_rcp_f32_e32 v16, v16
	v_rcp_f32_e32 v17, v17
	v_pk_mul_f32 v[4:5], v[4:5], v[146:147] op_sel_hi:[1,0]
	v_pk_mul_f32 v[12:13], v[12:13], v[18:19]
	v_pk_mul_f32 v[10:11], v[10:11], v[146:147] op_sel_hi:[1,0]
	v_pk_mul_f32 v[14:15], v[14:15], v[16:17]
	v_pk_mul_f32 v[6:7], v[6:7], v[12:13]
	v_mul_f32_e32 v12, 0xbfb8aa3b, v8
	v_mul_f32_e32 v13, 0xbfb8aa3b, v9
	v_pk_mul_f32 v[4:5], v[4:5], v[14:15]
	v_exp_f32_e32 v12, v12
	v_exp_f32_e32 v13, v13
	v_mul_f32_e32 v14, 0xbfb8aa3b, v10
	v_mul_f32_e32 v15, 0xbfb8aa3b, v11
	v_exp_f32_e32 v14, v14
	v_exp_f32_e32 v15, v15
	v_add_f32_e32 v12, 1.0, v12
	v_add_f32_e32 v13, 1.0, v13
	v_rcp_f32_e32 v12, v12
	v_rcp_f32_e32 v13, v13
	v_add_f32_e32 v14, 1.0, v14
	v_add_f32_e32 v15, 1.0, v15
	v_rcp_f32_e32 v14, v14
	v_rcp_f32_e32 v15, v15
	v_pk_mul_f32 v[0:1], v[0:1], v[146:147] op_sel_hi:[1,0]
	v_pk_mul_f32 v[8:9], v[8:9], v[12:13]
	v_pk_mul_f32 v[2:3], v[2:3], v[146:147] op_sel_hi:[1,0]
	v_pk_mul_f32 v[8:9], v[0:1], v[8:9]
	v_pk_mul_f32 v[0:1], v[10:11], v[14:15]
	v_add_u32_e32 v12, 0xb0, v144
	v_pk_mul_f32 v[10:11], v[2:3], v[0:1]
	v_cvt_pk_bf16_f32 v0, v4, v5
	v_mad_i64_i32 v[4:5], s[28:29], v12, s68, v[108:109]
	v_cvt_pk_bf16_f32 v1, v6, v7
	v_cvt_pk_bf16_f32 v2, v8, v9
	v_cvt_pk_bf16_f32 v3, v10, v11
	v_lshl_add_u64 v[4:5], v[4:5], 0, v[110:111]
	global_store_dwordx4 v[4:5], v[0:3], off
	s_cbranch_scc1 .LBB0_1226
	s_waitcnt vmcnt(0)
	buffer_wbl2 sc1
	s_waitcnt vmcnt(0)
	s_waitcnt vmcnt(0)
	s_and_saveexec_b64 s[28:29], s[4:5]
	s_cbranch_execz .LBB0_1225
	s_mov_b64 s[30:31], exec
	v_mbcnt_lo_u32_b32 v0, s30, 0
	v_mbcnt_hi_u32_b32 v0, s31, v0
	v_cmp_eq_u32_e32 vcc, 0, v0
	s_and_b64 s[34:35], exec, vcc
	s_mov_b64 exec, s[34:35]
	s_cbranch_execz .LBB0_1225
	s_bcnt1_i32_b64 s11, s[30:31]
	v_mov_b32_e32 v0, s11
	global_atomic_add v129, v0, s[8:9]
	s_branch .LBB0_1225
